# x->f16 conversion loop: 16 loads in flight per wave instead of serialized load/wait/store
# baseline (speedup 1.0000x reference)
; __device__ __forceinline__ unsigned cvt_pk_f16(float lo, float hi) { typedef _Float16 h2 __attribute__((ext_vector_type(2))); const h2 v = {(_Float16)lo, (_Float16)hi}; return __builtin_bit_cast(unsigned, v); }
; __global__ void __launch_bounds__(512, 2) fwd_kernel(Args args) {
;     ...
;         for (int m = gw; m < NTOK; m += ngw) {
;             const f32x4* xr = (const f32x4*)(x + (size_t)m * DM) + lane; u32x2* o8 = (u32x2*)(HB + (size_t)m * DM) + lane;
; #pragma unroll
;             for (int j = 0; j < 4; ++j) { const f32x4 v = xr[64 * j]; u32x2 w; w.x = pg8::cvt_pk_f16(v.x, v.y); w.y = pg8::cvt_pk_f16(v.z, v.w); o8[64 * j] = w; }
;         }
.LBB0_58:
	global_load_dwordx4 v[100:103], v[4:5], off offset:-2048
	global_load_dwordx4 v[104:107], v[4:5], off offset:-1024
	global_load_dwordx4 v[108:111], v[4:5], off
	global_load_dwordx4 v[112:115], v[4:5], off offset:1024
	v_lshl_add_u64 v[88:89], v[4:5], 0, s[8:9]
	global_load_dwordx4 v[116:119], v[88:89], off offset:-2048
	global_load_dwordx4 v[120:123], v[88:89], off offset:-1024
	global_load_dwordx4 v[124:127], v[88:89], off
	global_load_dwordx4 v[128:131], v[88:89], off offset:1024
	v_lshl_add_u64 v[90:91], v[88:89], 0, s[8:9]
	global_load_dwordx4 v[132:135], v[90:91], off offset:-2048
	global_load_dwordx4 v[136:139], v[90:91], off offset:-1024
	global_load_dwordx4 v[140:143], v[90:91], off
	global_load_dwordx4 v[144:147], v[90:91], off offset:1024
	v_lshl_add_u64 v[92:93], v[90:91], 0, s[8:9]
	global_load_dwordx4 v[148:151], v[92:93], off offset:-2048
	global_load_dwordx4 v[152:155], v[92:93], off offset:-1024
	global_load_dwordx4 v[156:159], v[92:93], off
	global_load_dwordx4 v[160:163], v[92:93], off offset:1024
	v_lshl_add_u64 v[94:95], v[2:3], 0, s[0:1]
	v_lshl_add_u64 v[96:97], v[94:95], 0, s[0:1]
	v_lshl_add_u64 v[98:99], v[96:97], 0, s[0:1]
	v_lshl_add_u64 v[4:5], v[92:93], 0, s[8:9]
	s_waitcnt vmcnt(15)
	v_cvt_pk_f16_f32 v100, v100, v101
	v_cvt_pk_f16_f32 v101, v102, v103
	global_store_dwordx2 v[2:3], v[100:101], off offset:-1536
	s_waitcnt vmcnt(15)
	v_cvt_pk_f16_f32 v104, v104, v105
	v_cvt_pk_f16_f32 v105, v106, v107
	global_store_dwordx2 v[2:3], v[104:105], off offset:-1024
	s_waitcnt vmcnt(15)
	v_cvt_pk_f16_f32 v108, v108, v109
	v_cvt_pk_f16_f32 v109, v110, v111
	global_store_dwordx2 v[2:3], v[108:109], off offset:-512
	s_waitcnt vmcnt(15)
	v_cvt_pk_f16_f32 v112, v112, v113
	v_cvt_pk_f16_f32 v113, v114, v115
	global_store_dwordx2 v[2:3], v[112:113], off
	s_waitcnt vmcnt(15)
	v_cvt_pk_f16_f32 v116, v116, v117
	v_cvt_pk_f16_f32 v117, v118, v119
	global_store_dwordx2 v[94:95], v[116:117], off offset:-1536
	s_waitcnt vmcnt(15)
	v_cvt_pk_f16_f32 v120, v120, v121
	v_cvt_pk_f16_f32 v121, v122, v123
	global_store_dwordx2 v[94:95], v[120:121], off offset:-1024
	s_waitcnt vmcnt(15)
	v_cvt_pk_f16_f32 v124, v124, v125
	v_cvt_pk_f16_f32 v125, v126, v127
	global_store_dwordx2 v[94:95], v[124:125], off offset:-512
	s_waitcnt vmcnt(15)
	v_cvt_pk_f16_f32 v128, v128, v129
	v_cvt_pk_f16_f32 v129, v130, v131
	global_store_dwordx2 v[94:95], v[128:129], off
	s_waitcnt vmcnt(15)
	v_cvt_pk_f16_f32 v132, v132, v133
	v_cvt_pk_f16_f32 v133, v134, v135
	global_store_dwordx2 v[96:97], v[132:133], off offset:-1536
	s_waitcnt vmcnt(15)
	v_cvt_pk_f16_f32 v136, v136, v137
	v_cvt_pk_f16_f32 v137, v138, v139
	global_store_dwordx2 v[96:97], v[136:137], off offset:-1024
	s_waitcnt vmcnt(15)
	v_cvt_pk_f16_f32 v140, v140, v141
	v_cvt_pk_f16_f32 v141, v142, v143
	global_store_dwordx2 v[96:97], v[140:141], off offset:-512
	s_waitcnt vmcnt(15)
	v_cvt_pk_f16_f32 v144, v144, v145
	v_cvt_pk_f16_f32 v145, v146, v147
	global_store_dwordx2 v[96:97], v[144:145], off
	s_waitcnt vmcnt(15)
	v_cvt_pk_f16_f32 v148, v148, v149
	v_cvt_pk_f16_f32 v149, v150, v151
	global_store_dwordx2 v[98:99], v[148:149], off offset:-1536
	s_waitcnt vmcnt(15)
	v_cvt_pk_f16_f32 v152, v152, v153
	v_cvt_pk_f16_f32 v153, v154, v155
	global_store_dwordx2 v[98:99], v[152:153], off offset:-1024
	s_waitcnt vmcnt(15)
	v_cvt_pk_f16_f32 v156, v156, v157
	v_cvt_pk_f16_f32 v157, v158, v159
	global_store_dwordx2 v[98:99], v[156:157], off offset:-512
	s_waitcnt vmcnt(15)
	v_cvt_pk_f16_f32 v160, v160, v161
	v_cvt_pk_f16_f32 v161, v162, v163
	global_store_dwordx2 v[98:99], v[160:161], off
	v_lshl_add_u64 v[2:3], v[98:99], 0, s[0:1]
	s_add_i32 s6, s6, s66
	s_add_i32 s6, s6, s66
	s_add_i32 s6, s6, s66
	s_add_i32 s6, s6, s66
	s_cmp_gt_i32 s6, 0xffff
	s_cbranch_scc0 .LBB0_58
